# RG-LRU gate loops: wave 4-7 stagger raised to s_sleep 32 (~2048 clk, about half an s-step)
# baseline (speedup 1.0000x reference)
; #define LAS __attribute__((address_space(3)))
; __device__ __forceinline__ unsigned cvt_pk_bf16(float lo, float hi) { unsigned r; asm volatile("v_cvt_pk_bf16_f32 %0, %1, %2" : "=v"(r) : "v"(lo), "v"(hi)); return r; }
; __device__ __forceinline__ float bflo(unsigned w) { return __uint_as_float(w << 16); }
; __device__ __forceinline__ float bfhi(unsigned w) { return __uint_as_float(w & 0xffff0000u); }
; __device__ __forceinline__ int lru_perm(int t) { return (t & ~63) | ((t & 12) << 2) | ((t & 48) >> 2) | (t & 3); }
; template <bool PASS2>
; __device__ __forceinline__ void lru_item(const Frame& F, const Args& a, int item) {
;     ...
;         for (int it = 0; it < 8; ++it) { const int tl = r0 + 32 * it;
;             f32x4 x0 = cbv[0], x1 = cbv[1];
; #pragma unroll
;             for (int j = 0; j < 4; ++j) { const u32x4 v = *(const LAS u32x4*)(R0 + (tl + j) * AT_PITCH + 16 * cch);
;                 x0[0] += cw[j][0][0] * bflo(v.x); x0[1] += cw[j][0][1] * bfhi(v.x); x0[2] += cw[j][0][2] * bflo(v.y); x0[3] += cw[j][0][3] * bfhi(v.y);
;                 x1[0] += cw[j][1][0] * bflo(v.z); x1[1] += cw[j][1][1] * bfhi(v.z); x1[2] += cw[j][1][2] * bflo(v.w); x1[3] += cw[j][1][3] * bfhi(v.w); }
;             u32x4 o; o.x = cvt_pk_bf16(x0[0], x0[1]); o.y = cvt_pk_bf16(x0[2], x0[3]); o.z = cvt_pk_bf16(x1[0], x1[1]); o.w = cvt_pk_bf16(x1[2], x1[3]);
;             *(LAS u32x4*)(AT + lru_perm(tl) * AT_PITCH + 16 * cch) = o; }
.LBB0_148:
	v_add_u32_e32 v84, s5, v113
	ds_read_b128 v[46:49], v84
	ds_read_b128 v[50:53], v84 offset:272
	ds_read_b128 v[54:57], v84 offset:544
	ds_read_b128 v[58:61], v84 offset:816
	v_and_or_b32 v62, v45, s49, v111
	v_add_u32_e32 v64, 32, v45
	v_mad_u64_u32 v[62:63], s[6:7], v62, s45, v[100:101]
	v_and_b32_e32 v65, 12, v44
	v_and_b32_e32 v63, 0xfffffc3, v64
	s_waitcnt lgkmcnt(2)
	v_lshlrev_b32_e32 v67, 16, v50
	v_lshlrev_b32_e32 v66, 16, v46
	v_and_b32_e32 v69, 0xffff0000, v50
	v_and_b32_e32 v68, 0xffff0000, v46
	v_or3_b32 v63, v63, v65, v109
	v_lshlrev_b32_e32 v71, 16, v51
	v_lshlrev_b32_e32 v70, 16, v47
	v_and_b32_e32 v51, 0xffff0000, v51
	v_and_b32_e32 v50, 0xffff0000, v47
	v_lshlrev_b32_e32 v47, 16, v52
	v_lshlrev_b32_e32 v46, 16, v48
	v_and_b32_e32 v73, 0xffff0000, v52
	v_and_b32_e32 v72, 0xffff0000, v48
	v_lshlrev_b32_e32 v75, 16, v53
	v_lshlrev_b32_e32 v74, 16, v49
	v_and_b32_e32 v53, 0xffff0000, v53
	v_and_b32_e32 v52, 0xffff0000, v49
	s_waitcnt lgkmcnt(0)
	v_lshlrev_b32_e32 v49, 16, v58
	v_lshlrev_b32_e32 v48, 16, v54
	v_and_b32_e32 v77, 0xffff0000, v58
	v_and_b32_e32 v76, 0xffff0000, v54
	v_lshlrev_b32_e32 v78, 16, v55
	v_and_b32_e32 v58, 0xffff0000, v55
	v_lshlrev_b32_e32 v55, 16, v60
	v_lshlrev_b32_e32 v54, 16, v56
	v_and_b32_e32 v81, 0xffff0000, v60
	v_and_b32_e32 v80, 0xffff0000, v56
	v_lshlrev_b32_e32 v82, 16, v57
	v_and_b32_e32 v60, 0xffff0000, v57
	v_pk_mul_f32 v[56:57], v[34:35], v[66:67]
	v_pk_mul_f32 v[66:67], v[4:5], v[68:69]
	v_mad_u64_u32 v[64:65], s[6:7], v63, s45, v[100:101]
	v_pk_mul_f32 v[68:69], v[32:33], v[70:71]
	v_pk_mul_f32 v[50:51], v[6:7], v[50:51]
	v_pk_mul_f32 v[46:47], v[30:31], v[46:47]
	v_pk_mul_f32 v[70:71], v[8:9], v[72:73]
	v_pk_mul_f32 v[72:73], v[28:29], v[74:75]
	v_pk_mul_f32 v[52:53], v[10:11], v[52:53]
	s_waitcnt vmcnt(1)
	v_add_f32_e32 v56, v20, v56
	v_add_f32_e32 v63, v21, v66
	v_lshlrev_b32_e32 v79, 16, v59
	v_and_b32_e32 v59, 0xffff0000, v59
	v_lshlrev_b32_e32 v83, 16, v61
	v_and_b32_e32 v61, 0xffff0000, v61
	v_pk_mul_f32 v[48:49], v[42:43], v[48:49]
	v_pk_mul_f32 v[74:75], v[16:17], v[76:77]
	v_add_f32_e32 v65, v22, v68
	v_add_f32_e32 v50, v23, v50
	s_waitcnt vmcnt(0)
	v_add_f32_e32 v46, v24, v46
	v_add_f32_e32 v66, v25, v70
	v_add_f32_e32 v68, v26, v72
	v_add_f32_e32 v52, v27, v52
	v_add_f32_e32 v56, v56, v57
	v_add_f32_e32 v57, v63, v67
	v_pk_mul_f32 v[76:77], v[40:41], v[78:79]
	v_pk_mul_f32 v[58:59], v[18:19], v[58:59]
	v_pk_mul_f32 v[54:55], v[38:39], v[54:55]
	v_pk_mul_f32 v[78:79], v[12:13], v[80:81]
	v_pk_mul_f32 v[80:81], v[36:37], v[82:83]
	v_pk_mul_f32 v[60:61], v[14:15], v[60:61]
	v_add_f32_e32 v63, v65, v69
	v_add_f32_e32 v50, v50, v51
	v_add_f32_e32 v46, v46, v47
	v_add_f32_e32 v47, v66, v71
	v_add_f32_e32 v51, v68, v73
	v_add_f32_e32 v52, v52, v53
	v_add_f32_e32 v48, v56, v48
	v_add_f32_e32 v53, v57, v74
	v_add_f32_e32 v56, v63, v76
	v_add_f32_e32 v50, v50, v58
	v_add_f32_e32 v46, v46, v54
	v_add_f32_e32 v47, v47, v78
	v_add_f32_e32 v51, v51, v80
	v_add_f32_e32 v52, v52, v60
	v_add_f32_e32 v48, v48, v49
	v_add_f32_e32 v49, v53, v75
	v_add_f32_e32 v53, v56, v77
	v_add_f32_e32 v50, v50, v59
	v_add_f32_e32 v54, v46, v55
	v_add_f32_e32 v55, v47, v79
	v_add_f32_e32 v51, v51, v81
	v_add_f32_e32 v52, v52, v61
	v_cvt_pk_bf16_f32 v46, v48, v49
	v_cvt_pk_bf16_f32 v47, v53, v50
	v_cvt_pk_bf16_f32 v48, v54, v55
	v_cvt_pk_bf16_f32 v49, v51, v52
	ds_write_b128 v62, v[46:49]
	ds_read_b128 v[46:49], v84 offset:8976
	ds_read_b128 v[50:53], v84 offset:8704
	ds_read_b128 v[54:57], v84 offset:9248
	ds_read_b128 v[58:61], v84 offset:9520
	s_addk_i32 s5, 0x4400
	s_waitcnt lgkmcnt(3)
	v_lshlrev_b32_e32 v63, 16, v46
	s_waitcnt lgkmcnt(2)
	v_lshlrev_b32_e32 v62, 16, v50
	v_and_b32_e32 v67, 0xffff0000, v46
	v_and_b32_e32 v66, 0xffff0000, v50
	v_lshlrev_b32_e32 v69, 16, v47
	v_lshlrev_b32_e32 v68, 16, v51
	v_and_b32_e32 v47, 0xffff0000, v47
	v_and_b32_e32 v46, 0xffff0000, v51
	v_lshlrev_b32_e32 v51, 16, v48
	v_lshlrev_b32_e32 v50, 16, v52
	v_and_b32_e32 v71, 0xffff0000, v48
	v_and_b32_e32 v70, 0xffff0000, v52
	v_lshlrev_b32_e32 v73, 16, v49
	v_lshlrev_b32_e32 v72, 16, v53
	v_and_b32_e32 v49, 0xffff0000, v49
	v_and_b32_e32 v48, 0xffff0000, v53
	s_waitcnt lgkmcnt(0)
	v_lshlrev_b32_e32 v53, 16, v58
	v_lshlrev_b32_e32 v52, 16, v54
	v_and_b32_e32 v75, 0xffff0000, v58
	v_and_b32_e32 v74, 0xffff0000, v54
	v_lshlrev_b32_e32 v76, 16, v55
	v_and_b32_e32 v58, 0xffff0000, v55
	v_lshlrev_b32_e32 v55, 16, v60
	v_lshlrev_b32_e32 v54, 16, v56
	v_and_b32_e32 v79, 0xffff0000, v60
	v_and_b32_e32 v78, 0xffff0000, v56
	v_lshlrev_b32_e32 v80, 16, v57
	v_and_b32_e32 v60, 0xffff0000, v57
	v_pk_mul_f32 v[56:57], v[34:35], v[62:63]
	v_pk_mul_f32 v[62:63], v[4:5], v[66:67]
	v_pk_mul_f32 v[66:67], v[32:33], v[68:69]
	v_pk_mul_f32 v[46:47], v[6:7], v[46:47]
	v_pk_mul_f32 v[50:51], v[30:31], v[50:51]
	v_pk_mul_f32 v[68:69], v[8:9], v[70:71]
	v_pk_mul_f32 v[70:71], v[28:29], v[72:73]
	v_pk_mul_f32 v[48:49], v[10:11], v[48:49]
	v_add_f32_e32 v56, v20, v56
	v_lshlrev_b32_e32 v77, 16, v59
	v_and_b32_e32 v59, 0xffff0000, v59
	v_lshlrev_b32_e32 v81, 16, v61
	v_and_b32_e32 v61, 0xffff0000, v61
	v_pk_mul_f32 v[52:53], v[42:43], v[52:53]
	v_add_f32_e32 v62, v21, v62
	v_add_f32_e32 v65, v22, v66
	v_add_f32_e32 v46, v23, v46
	v_add_f32_e32 v50, v24, v50
	v_add_f32_e32 v66, v25, v68
	v_add_f32_e32 v68, v26, v70
	v_add_f32_e32 v48, v27, v48
	v_add_f32_e32 v56, v56, v57
	v_pk_mul_f32 v[72:73], v[16:17], v[74:75]
	v_pk_mul_f32 v[74:75], v[40:41], v[76:77]
	v_pk_mul_f32 v[58:59], v[18:19], v[58:59]
	v_pk_mul_f32 v[54:55], v[38:39], v[54:55]
	v_pk_mul_f32 v[76:77], v[12:13], v[78:79]
	v_pk_mul_f32 v[78:79], v[36:37], v[80:81]
	v_pk_mul_f32 v[60:61], v[14:15], v[60:61]
	v_add_f32_e32 v57, v62, v63
	v_add_f32_e32 v62, v65, v67
	v_add_f32_e32 v46, v46, v47
	v_add_f32_e32 v47, v50, v51
	v_add_f32_e32 v50, v66, v69
	v_add_f32_e32 v51, v68, v71
	v_add_f32_e32 v48, v48, v49
	v_add_f32_e32 v49, v56, v52
	v_add_u32_e32 v45, 64, v45
	v_add_u32_e32 v44, 16, v44
	s_cmp_eq_u32 s5, 0x11000
	v_add_f32_e32 v52, v57, v72
	v_add_f32_e32 v56, v62, v74
	v_add_f32_e32 v46, v46, v58
	v_add_f32_e32 v47, v47, v54
	v_add_f32_e32 v50, v50, v76
	v_add_f32_e32 v51, v51, v78
	v_add_f32_e32 v48, v48, v60
	v_add_f32_e32 v49, v49, v53
	v_add_f32_e32 v52, v52, v73
	v_add_f32_e32 v53, v56, v75
	v_add_f32_e32 v54, v46, v59
	v_add_f32_e32 v55, v47, v55
	v_add_f32_e32 v50, v50, v77
	v_add_f32_e32 v51, v51, v79
	v_add_f32_e32 v56, v48, v61
	v_cvt_pk_bf16_f32 v46, v49, v52
	v_cvt_pk_bf16_f32 v47, v53, v54
	v_cvt_pk_bf16_f32 v48, v55, v50
	v_cvt_pk_bf16_f32 v49, v51, v56
	ds_write_b128 v64, v[46:49]
	s_cbranch_scc0 .LBB0_148
; #define LAS __attribute__((address_space(3)))
; template <bool PASS2>
; __device__ __forceinline__ void lru_item(const Frame& F, const Args& a, int item) {
;     ...
;         __syncthreads();
;         if (PASS2) {
; #pragma unroll
;             for (int it = 0; it < 8; ++it) *(LAS u32x4*)(R0 + (r0 + 32 * it) * AT_PITCH + 16 * cch) = ybv[it];
;         }
;     }
;     bf16x8 sel;
;     { const bool mine = (fq == 2 * (w & 1) + (fr >> 3));
; #pragma unroll
;       for (int jj = 0; jj < 8; ++jj) sel[jj] = (mine && jj == (fr & 7)) ? (short)0x3F80 : (short)0; }
;     const int ks0 = w >> 1;
;     float hf[4][4][4];
; #pragma unroll
;     for (int i0 = 0; i0 < 4; ++i0)
; #pragma unroll
;         for (int i1 = 0; i1 < 4; ++i1)
; #pragma unroll
;             for (int i2 = 0; i2 < 4; ++i2) hf[i0][i1][i2] = 0.f;
;     auto dir_body = [&](auto dirc) __attribute__((always_inline)) { constexpr int dir = decltype(dirc)::value;
;         const bf16_t* wt = (const bf16_t*)(a.ws + WS_WLRU) + (size_t)((dir * 12 + n) * 2) * 16384 + (size_t)c * 128 + 8 * fq;
;         bf16x8 wrf[4], wif[4];
; #pragma unroll
;         for (int ks = 0; ks < 4; ++ks) { wrf[ks] = *(const bf16x8*)(wt + 32 * ks); wif[ks] = *(const bf16x8*)(wt + 16384 + 32 * ks); }
;         const float ba = a.lru_ba[dir * 1536 + cg_], bi = a.lru_bi[dir * 1536 + cg_];
;         const float lam = a.lru_lambda[dir * 1536 + cg_];
;         const float logu = -8.0f * log1pf(__expf(-lam));
;         float hc = 0.f, TA = 1.f, TB = 0.f;
;         if (PASS2) { const f32x2* ag = (const f32x2*)(a.ws + WS_AGG) + ((size_t)(b * NCHUNK) * 2 + dir) * 1536 + cg_;
;             f32x2 pa[NCHUNK];
; #pragma unroll
;             for (int cc = 0; cc < NCHUNK; ++cc) pa[cc] = ag[(size_t)cc * 2 * 1536];
; #pragma unroll
;             for (int i = 0; i < NCHUNK; ++i) { const int cc = dir ? NCHUNK - 1 - i : i; const bool use = dir ? (cc > chunk) : (cc < chunk); if (use) hc = pa[cc].x * hc + pa[cc].y; } }
;         const int tstart = dir ? SEQ - 1 : 0;
;         if (dir == 1) __syncthreads();
; #pragma unroll 1
;         for (int si = 0; si < 4; ++si) { const int s = dir ? 3 - si : si;
	v_add_u32_e32 v104, s4, v92
	v_ashrrev_i32_e32 v105, 31, v104
	v_readlane_b32 s60, v242, 17
	v_lshlrev_b64 v[4:5], 2, v[104:105]
	v_readlane_b32 s61, v242, 18
	s_waitcnt lgkmcnt(0)
	s_barrier
	v_lshl_add_u64 v[6:7], s[60:61], 0, v[4:5]
	s_waitcnt vmcnt(0)
	v_mov_b32_e32 v26, v178
	s_lshl_b32 s40, s13, 1
	s_ashr_i32 s41, s40, 31
	s_lshl_b64 s[4:5], s[40:41], 15
	v_lshl_add_u64 v[20:21], v[102:103], 0, s[4:5]
	v_lshl_add_u64 v[22:23], s[86:87], 0, v[4:5]
	v_lshl_add_u64 v[24:25], s[90:91], 0, v[4:5]
	v_add_co_u32_e32 v32, vcc, 0x8000, v20
	v_mov_b32_e32 v4, v146
	v_mov_b32_e32 v5, v147
	v_mov_b32_e32 v6, v148
	v_mov_b32_e32 v7, v149
	v_mov_b32_e32 v8, v150
	v_mov_b32_e32 v9, v151
	v_mov_b32_e32 v10, v152
	v_mov_b32_e32 v11, v153
	v_mov_b32_e32 v12, v154
	v_mov_b32_e32 v13, v155
	v_mov_b32_e32 v14, v156
	v_mov_b32_e32 v15, v157
	v_mov_b32_e32 v16, v158
	v_mov_b32_e32 v17, v159
	v_mov_b32_e32 v18, v160
	v_mov_b32_e32 v19, v161
	v_mov_b32_e32 v128, v179
	v_mov_b32_e32 v130, v180
	v_addc_co_u32_e32 v33, vcc, 0, v21, vcc
	s_mov_b32 s39, 0
	v_mov_b32_e32 v106, 1.0
	v_or_b32_e32 v124, 64, v122
	v_or_b32_e32 v125, 0x80, v122
	v_or_b32_e32 v126, 0xc0, v122
	v_add_u32_e32 v127, s57, v93
	v_mov_b32_e32 v129, 0
	v_mov_b32_e32 v132, v116
	v_readlane_b32 s62, v242, 19
	v_readlane_b32 s63, v242, 20
	v_readlane_b32 s64, v242, 21
	v_readlane_b32 s65, v242, 22
	v_readlane_b32 s66, v242, 23
	v_readlane_b32 s67, v242, 24
	v_readlane_b32 s68, v242, 25
	v_readlane_b32 s69, v242, 26
	v_readlane_b32 s70, v242, 27
	v_readlane_b32 s71, v242, 28
	v_readlane_b32 s72, v242, 29
	v_readlane_b32 s73, v242, 30
	v_readlane_b32 s74, v242, 31
	v_readlane_b32 s75, v242, 32
	s_waitcnt vmcnt(6)
	v_mul_f32_e32 v20, 0xbfb8aa3b, v26
	v_exp_f32_e32 v38, v20
	v_mov_b32_e32 v20, v162
	v_mov_b32_e32 v21, v163
	v_mov_b32_e32 v22, v164
	v_mov_b32_e32 v23, v165
	v_mov_b32_e32 v24, v166
	v_mov_b32_e32 v25, v167
	v_mov_b32_e32 v26, v168
	v_mov_b32_e32 v27, v169
	v_mov_b32_e32 v28, v170
	v_mov_b32_e32 v29, v171
	v_mov_b32_e32 v30, v172
	v_mov_b32_e32 v31, v173
	s_nop 0
	v_mov_b32_e32 v32, v174
	v_mov_b32_e32 v33, v175
	v_mov_b32_e32 v34, v176
	v_mov_b32_e32 v35, v177
	v_add_f32_e32 v39, 1.0, v38
	v_add_f32_e32 v40, -1.0, v39
	v_frexp_mant_f32_e32 v41, v39
	v_cvt_f64_f32_e32 v[36:37], v39
	v_sub_f32_e32 v42, v40, v39
	v_frexp_exp_i32_f64_e32 v36, v[36:37]
	v_cmp_gt_f32_e32 vcc, s50, v41
	v_sub_f32_e32 v40, v38, v40
	v_add_f32_e32 v37, 1.0, v42
	v_subbrev_co_u32_e32 v36, vcc, 0, v36, vcc
	v_add_f32_e32 v37, v40, v37
	v_sub_u32_e32 v40, 0, v36
	v_cvt_f32_i32_e32 v36, v36
	v_ldexp_f32 v39, v39, v40
	v_ldexp_f32 v37, v37, v40
	v_add_f32_e32 v40, -1.0, v39
	v_add_f32_e32 v41, 1.0, v39
	v_add_f32_e32 v42, 1.0, v40
	v_add_f32_e32 v43, -1.0, v41
	v_sub_f32_e32 v42, v39, v42
	v_sub_f32_e32 v39, v39, v43
	v_mul_f32_e32 v43, 0x3f317218, v36
	v_add_f32_e32 v42, v37, v42
	v_add_f32_e32 v37, v37, v39
	v_fma_f32 v39, v36, s51, -v43
	v_add_f32_e32 v44, v40, v42
	v_add_f32_e32 v45, v41, v37
	v_fmac_f32_e32 v39, 0xb102e308, v36
	v_sub_f32_e32 v36, v44, v40
	v_sub_f32_e32 v40, v45, v41
	v_rcp_f32_e32 v41, v45
	v_add_f32_e32 v46, v43, v39
	v_sub_f32_e32 v37, v37, v40
	v_sub_f32_e32 v40, v46, v43
	v_sub_f32_e32 v39, v39, v40
	v_mul_f32_e32 v40, v44, v41
	v_sub_f32_e32 v36, v42, v36
	v_mul_f32_e32 v42, v45, v40
	v_fma_f32 v43, v40, v45, -v42
	v_fmac_f32_e32 v43, v40, v37
	v_add_f32_e32 v47, v42, v43
	v_sub_f32_e32 v48, v44, v47
	v_sub_f32_e32 v42, v47, v42
	v_sub_f32_e32 v44, v44, v48
	v_sub_f32_e32 v42, v42, v43
	v_sub_f32_e32 v43, v44, v47
	v_add_f32_e32 v36, v36, v43
	v_add_f32_e32 v36, v42, v36
	v_add_f32_e32 v42, v48, v36
	v_mul_f32_e32 v43, v41, v42
	v_sub_f32_e32 v44, v48, v42
	v_mul_f32_e32 v47, v45, v43
	v_add_f32_e32 v36, v36, v44
	v_add_f32_e32 v44, v40, v43
	v_fma_f32 v45, v43, v45, -v47
	v_sub_f32_e32 v40, v44, v40
	v_fmac_f32_e32 v45, v43, v37
	v_sub_f32_e32 v37, v43, v40
	v_add_f32_e32 v40, v47, v45
	v_sub_f32_e32 v43, v40, v47
	v_sub_f32_e32 v47, v42, v40
	v_sub_f32_e32 v42, v42, v47
	v_sub_f32_e32 v40, v42, v40
	v_sub_f32_e32 v43, v43, v45
	v_add_f32_e32 v36, v36, v40
	v_add_f32_e32 v36, v43, v36
	v_add_f32_e32 v36, v47, v36
	v_mul_f32_e32 v36, v41, v36
	v_add_f32_e32 v36, v37, v36
	v_add_f32_e32 v37, v44, v36
	v_mul_f32_e32 v40, v37, v37
	v_fmamk_f32 v43, v40, 0x3e9b6dac, v117
	v_sub_f32_e32 v41, v37, v44
	v_ldexp_f32 v42, v37, 1
	v_mul_f32_e32 v37, v37, v40
	v_fmaak_f32 v40, v40, v43, 0x3f2aaada
	v_mul_f32_e32 v37, v37, v40
	v_add_f32_e32 v40, v42, v37
	v_sub_f32_e32 v36, v36, v41
	v_sub_f32_e32 v41, v40, v42
	v_ldexp_f32 v36, v36, 1
	v_sub_f32_e32 v37, v37, v41
	v_add_f32_e32 v36, v36, v37
	v_add_f32_e32 v37, v40, v36
	v_sub_f32_e32 v40, v37, v40
	v_add_f32_e32 v41, v46, v37
	v_sub_f32_e32 v36, v36, v40
	v_sub_f32_e32 v40, v41, v46
	v_sub_f32_e32 v42, v41, v40
	v_sub_f32_e32 v37, v37, v40
	v_add_f32_e32 v40, v39, v36
	v_sub_f32_e32 v42, v46, v42
	v_sub_f32_e32 v43, v40, v39
	v_add_f32_e32 v37, v37, v42
	v_sub_f32_e32 v42, v40, v43
	v_sub_f32_e32 v36, v36, v43
	v_sub_f32_e32 v39, v39, v42
	v_add_f32_e32 v37, v40, v37
	v_add_f32_e32 v36, v36, v39
	v_add_f32_e32 v39, v41, v37
	v_sub_f32_e32 v40, v39, v41
	v_sub_f32_e32 v37, v37, v40
	v_add_f32_e32 v36, v36, v37
	v_add_f32_e32 v36, v39, v36
	v_cmp_neq_f32_e32 vcc, s52, v38
	s_nop 1
	v_cndmask_b32_e32 v36, v119, v36, vcc
	v_cmp_ngt_f32_e32 vcc, -1.0, v38
	s_nop 1
	v_cndmask_b32_e32 v36, v120, v36, vcc
	v_cmp_neq_f32_e32 vcc, -1.0, v38
	s_nop 1
	v_cndmask_b32_e32 v36, v121, v36, vcc
	v_cmp_lt_f32_e64 vcc, |v38|, s53
	s_nop 1
	v_cndmask_b32_e32 v36, v36, v38, vcc
	v_mul_f32_e32 v131, 0xc1000000, v36
	v_readfirstlane_b32 s98, v144
	s_cmp_lt_u32 s98, 0x100
	s_cbranch_scc1 .Lstag_150
	s_sleep 32

; template <bool PASS2>
; __device__ __forceinline__ void lru_item(const Frame& F, const Args& a, int item) {
;     ...
;         const bf16_t* wt = (const bf16_t*)(a.ws + WS_WLRU) + (size_t)((dir * 12 + n) * 2) * 16384 + (size_t)c * 128 + 8 * fq;
;         bf16x8 wrf[4], wif[4];
; #pragma unroll
;         for (int ks = 0; ks < 4; ++ks) { wrf[ks] = *(const bf16x8*)(wt + 32 * ks); wif[ks] = *(const bf16x8*)(wt + 16384 + 32 * ks); }
;         const float ba = a.lru_ba[dir * 1536 + cg_], bi = a.lru_bi[dir * 1536 + cg_];
;         const float lam = a.lru_lambda[dir * 1536 + cg_];
;         const float logu = -8.0f * log1pf(__expf(-lam));
;         float hc = 0.f, TA = 1.f, TB = 0.f;
;         if (PASS2) { const f32x2* ag = (const f32x2*)(a.ws + WS_AGG) + ((size_t)(b * NCHUNK) * 2 + dir) * 1536 + cg_;
;             f32x2 pa[NCHUNK];
; #pragma unroll
;             for (int cc = 0; cc < NCHUNK; ++cc) pa[cc] = ag[(size_t)cc * 2 * 1536];
; #pragma unroll
;             for (int i = 0; i < NCHUNK; ++i) { const int cc = dir ? NCHUNK - 1 - i : i; const bool use = dir ? (cc > chunk) : (cc < chunk); if (use) hc = pa[cc].x * hc + pa[cc].y; } }
;         const int tstart = dir ? SEQ - 1 : 0;
;         if (dir == 1) __syncthreads();
; #pragma unroll 1
;         for (int si = 0; si < 4; ++si) { const int s = dir ? 3 - si : si;
.LBB0_186:
	s_or_b64 exec, exec, s[14:15]
	v_add_u32_e32 v4, 0x600, v104
	v_mov_b32_e32 v5, v95
	v_readlane_b32 s60, v242, 17
	v_lshlrev_b64 v[4:5], 2, v[4:5]
	v_readlane_b32 s61, v242, 18
	s_add_i32 s14, s40, 24
	s_mov_b32 s15, s12
	v_lshl_add_u64 v[6:7], s[60:61], 0, v[4:5]
	v_mov_b32_e32 v36, v142
	s_lshl_b64 s[14:15], s[14:15], 15
	v_lshl_add_u64 v[20:21], v[102:103], 0, s[14:15]
	v_lshl_add_u64 v[22:23], s[86:87], 0, v[4:5]
	v_lshl_add_u64 v[24:25], s[90:91], 0, v[4:5]
	v_add_co_u32_e32 v32, vcc, 0x8000, v20
	v_mov_b32_e32 v4, v182
	v_mov_b32_e32 v5, v183
	v_mov_b32_e32 v6, v184
	v_mov_b32_e32 v7, v185
	v_mov_b32_e32 v8, v186
	v_mov_b32_e32 v9, v187
	v_mov_b32_e32 v10, v188
	v_mov_b32_e32 v11, v189
	v_mov_b32_e32 v12, v230
	v_mov_b32_e32 v13, v231
	v_mov_b32_e32 v14, v232
	v_mov_b32_e32 v15, v233
	v_mov_b32_e32 v16, v234
	v_mov_b32_e32 v17, v235
	v_mov_b32_e32 v18, v236
	v_mov_b32_e32 v19, v237
	v_mov_b32_e32 v128, v143
	v_mov_b32_e32 v129, v145
	v_addc_co_u32_e32 v33, vcc, 0, v21, vcc
	v_mov_b32_e32 v20, v238
	v_mov_b32_e32 v21, v239
	v_mov_b32_e32 v22, v240
	v_mov_b32_e32 v23, v241
	v_mov_b32_e32 v24, v134
	v_mov_b32_e32 v25, v135
	v_mov_b32_e32 v26, v136
	v_mov_b32_e32 v27, v137
	v_mov_b32_e32 v28, v138
	v_mov_b32_e32 v29, v139
	v_mov_b32_e32 v30, v140
	v_mov_b32_e32 v31, v141
	s_nop 0
	v_mov_b32_e32 v32, v244
	v_mov_b32_e32 v33, v245
	v_mov_b32_e32 v34, v246
	v_mov_b32_e32 v35, v247
	v_or_b32_e32 v127, s57, v93
	s_mov_b32 s39, 0
	v_mov_b32_e32 v106, 1.0
	v_mov_b32_e32 v131, 0
	v_readlane_b32 s62, v242, 19
	v_readlane_b32 s63, v242, 20
	v_readlane_b32 s64, v242, 21
	v_readlane_b32 s65, v242, 22
	v_readlane_b32 s66, v242, 23
	v_readlane_b32 s67, v242, 24
	v_readlane_b32 s68, v242, 25
	v_readlane_b32 s69, v242, 26
	v_readlane_b32 s70, v242, 27
	v_readlane_b32 s71, v242, 28
	v_readlane_b32 s72, v242, 29
	v_readlane_b32 s73, v242, 30
	v_readlane_b32 s74, v242, 31
	v_readlane_b32 s75, v242, 32
	s_barrier
	s_waitcnt vmcnt(10)
	v_mul_f32_e32 v36, 0xbfb8aa3b, v36
	v_exp_f32_e32 v38, v36
	s_nop 0
	v_add_f32_e32 v39, 1.0, v38
	v_add_f32_e32 v40, -1.0, v39
	v_frexp_mant_f32_e32 v41, v39
	v_cvt_f64_f32_e32 v[36:37], v39
	v_sub_f32_e32 v42, v40, v39
	v_frexp_exp_i32_f64_e32 v36, v[36:37]
	v_cmp_gt_f32_e32 vcc, s50, v41
	v_sub_f32_e32 v40, v38, v40
	v_add_f32_e32 v37, 1.0, v42
	v_subbrev_co_u32_e32 v36, vcc, 0, v36, vcc
	v_add_f32_e32 v37, v40, v37
	v_sub_u32_e32 v40, 0, v36
	v_cvt_f32_i32_e32 v36, v36
	v_ldexp_f32 v39, v39, v40
	v_ldexp_f32 v37, v37, v40
	v_add_f32_e32 v40, -1.0, v39
	v_add_f32_e32 v41, 1.0, v39
	v_add_f32_e32 v42, 1.0, v40
	v_add_f32_e32 v43, -1.0, v41
	v_sub_f32_e32 v42, v39, v42
	v_sub_f32_e32 v39, v39, v43
	v_mul_f32_e32 v43, 0x3f317218, v36
	v_add_f32_e32 v42, v37, v42
	v_add_f32_e32 v37, v37, v39
	v_fma_f32 v39, v36, s51, -v43
	v_add_f32_e32 v44, v40, v42
	v_add_f32_e32 v45, v41, v37
	v_fmac_f32_e32 v39, 0xb102e308, v36
	v_sub_f32_e32 v36, v44, v40
	v_sub_f32_e32 v40, v45, v41
	v_rcp_f32_e32 v41, v45
	v_add_f32_e32 v46, v43, v39
	v_sub_f32_e32 v37, v37, v40
	v_sub_f32_e32 v40, v46, v43
	v_sub_f32_e32 v39, v39, v40
	v_mul_f32_e32 v40, v44, v41
	v_sub_f32_e32 v36, v42, v36
	v_mul_f32_e32 v42, v45, v40
	v_fma_f32 v43, v40, v45, -v42
	v_fmac_f32_e32 v43, v40, v37
	v_add_f32_e32 v47, v42, v43
	v_sub_f32_e32 v48, v44, v47
	v_sub_f32_e32 v42, v47, v42
	v_sub_f32_e32 v44, v44, v48
	v_sub_f32_e32 v42, v42, v43
	v_sub_f32_e32 v43, v44, v47
	v_add_f32_e32 v36, v36, v43
	v_add_f32_e32 v36, v42, v36
	v_add_f32_e32 v42, v48, v36
	v_mul_f32_e32 v43, v41, v42
	v_sub_f32_e32 v44, v48, v42
	v_mul_f32_e32 v47, v45, v43
	v_add_f32_e32 v36, v36, v44
	v_add_f32_e32 v44, v40, v43
	v_fma_f32 v45, v43, v45, -v47
	v_sub_f32_e32 v40, v44, v40
	v_fmac_f32_e32 v45, v43, v37
	v_sub_f32_e32 v37, v43, v40
	v_add_f32_e32 v40, v47, v45
	v_sub_f32_e32 v43, v40, v47
	v_sub_f32_e32 v47, v42, v40
	v_sub_f32_e32 v42, v42, v47
	v_sub_f32_e32 v40, v42, v40
	v_sub_f32_e32 v43, v43, v45
	v_add_f32_e32 v36, v36, v40
	v_add_f32_e32 v36, v43, v36
	v_add_f32_e32 v36, v47, v36
	v_mul_f32_e32 v36, v41, v36
	v_add_f32_e32 v36, v37, v36
	v_add_f32_e32 v37, v44, v36
	v_mul_f32_e32 v40, v37, v37
	v_fmamk_f32 v43, v40, 0x3e9b6dac, v117
	v_sub_f32_e32 v41, v37, v44
	v_ldexp_f32 v42, v37, 1
	v_mul_f32_e32 v37, v37, v40
	v_fmaak_f32 v40, v40, v43, 0x3f2aaada
	v_mul_f32_e32 v37, v37, v40
	v_add_f32_e32 v40, v42, v37
	v_sub_f32_e32 v36, v36, v41
	v_sub_f32_e32 v41, v40, v42
	v_ldexp_f32 v36, v36, 1
	v_sub_f32_e32 v37, v37, v41
	v_add_f32_e32 v36, v36, v37
	v_add_f32_e32 v37, v40, v36
	v_sub_f32_e32 v40, v37, v40
	v_add_f32_e32 v41, v46, v37
	v_sub_f32_e32 v36, v36, v40
	v_sub_f32_e32 v40, v41, v46
	v_sub_f32_e32 v42, v41, v40
	v_sub_f32_e32 v37, v37, v40
	v_add_f32_e32 v40, v39, v36
	v_sub_f32_e32 v42, v46, v42
	v_sub_f32_e32 v43, v40, v39
	v_add_f32_e32 v37, v37, v42
	v_sub_f32_e32 v42, v40, v43
	v_sub_f32_e32 v36, v36, v43
	v_sub_f32_e32 v39, v39, v42
	v_add_f32_e32 v37, v40, v37
	v_add_f32_e32 v36, v36, v39
	v_add_f32_e32 v39, v41, v37
	v_sub_f32_e32 v40, v39, v41
	v_sub_f32_e32 v37, v37, v40
	v_add_f32_e32 v36, v36, v37
	v_add_f32_e32 v36, v39, v36
	v_cmp_neq_f32_e32 vcc, s52, v38
	s_nop 1
	v_cndmask_b32_e32 v36, v119, v36, vcc
	v_cmp_ngt_f32_e32 vcc, -1.0, v38
	s_nop 1
	v_cndmask_b32_e32 v36, v120, v36, vcc
	v_cmp_neq_f32_e32 vcc, -1.0, v38
	s_nop 1
	v_cndmask_b32_e32 v36, v121, v36, vcc
	v_cmp_lt_f32_e64 vcc, |v38|, s53
	s_nop 1
	v_cndmask_b32_e32 v36, v36, v38, vcc
	v_mul_f32_e32 v130, 0xc1000000, v36
	v_readfirstlane_b32 s98, v144
	s_cmp_lt_u32 s98, 0x100
	s_cbranch_scc1 .Lstag_187
	s_sleep 32

; template <bool PASS2>
; __device__ __forceinline__ void lru_item(const Frame& F, const Args& a, int item) {
;     ...
;         const bf16_t* wt = (const bf16_t*)(a.ws + WS_WLRU) + (size_t)((dir * 12 + n) * 2) * 16384 + (size_t)c * 128 + 8 * fq;
;         bf16x8 wrf[4], wif[4];
; #pragma unroll
;         for (int ks = 0; ks < 4; ++ks) { wrf[ks] = *(const bf16x8*)(wt + 32 * ks); wif[ks] = *(const bf16x8*)(wt + 16384 + 32 * ks); }
;         const float ba = a.lru_ba[dir * 1536 + cg_], bi = a.lru_bi[dir * 1536 + cg_];
;         const float lam = a.lru_lambda[dir * 1536 + cg_];
;         const float logu = -8.0f * log1pf(__expf(-lam));
;         float hc = 0.f, TA = 1.f, TB = 0.f;
;         if (PASS2) { const f32x2* ag = (const f32x2*)(a.ws + WS_AGG) + ((size_t)(b * NCHUNK) * 2 + dir) * 1536 + cg_;
;             f32x2 pa[NCHUNK];
; #pragma unroll
;             for (int cc = 0; cc < NCHUNK; ++cc) pa[cc] = ag[(size_t)cc * 2 * 1536];
; #pragma unroll
;             for (int i = 0; i < NCHUNK; ++i) { const int cc = dir ? NCHUNK - 1 - i : i; const bool use = dir ? (cc > chunk) : (cc < chunk); if (use) hc = pa[cc].x * hc + pa[cc].y; } }
;         const int tstart = dir ? SEQ - 1 : 0;
;         if (dir == 1) __syncthreads();
; #pragma unroll 1
;         for (int si = 0; si < 4; ++si) { const int s = dir ? 3 - si : si;
.LBB0_707:
	s_waitcnt vmcnt(15)
	v_mul_f32_e32 v4, 0xbfb8aa3b, v125
	v_exp_f32_e32 v4, v4
	s_mov_b32 s8, 0x3f2aaaab
	s_cmp_gt_i32 s33, 1
	s_waitcnt vmcnt(13)
	v_fmac_f32_e32 v75, v74, v5
	v_add_f32_e32 v8, 1.0, v4
	v_frexp_mant_f32_e32 v10, v8
	v_cvt_f64_f32_e32 v[6:7], v8
	v_add_f32_e32 v9, -1.0, v8
	v_frexp_exp_i32_f64_e32 v6, v[6:7]
	v_cmp_gt_f32_e32 vcc, s8, v10
	v_sub_f32_e32 v11, v9, v8
	v_sub_f32_e32 v9, v4, v9
	v_subbrev_co_u32_e32 v6, vcc, 0, v6, vcc
	v_add_f32_e32 v11, 1.0, v11
	v_sub_u32_e32 v7, 0, v6
	v_add_f32_e32 v9, v9, v11
	v_ldexp_f32 v8, v8, v7
	v_ldexp_f32 v7, v9, v7
	v_add_f32_e32 v9, -1.0, v8
	v_add_f32_e32 v12, 1.0, v8
	v_add_f32_e32 v10, 1.0, v9
	v_add_f32_e32 v13, -1.0, v12
	v_sub_f32_e32 v10, v8, v10
	v_sub_f32_e32 v8, v8, v13
	v_add_f32_e32 v10, v7, v10
	v_add_f32_e32 v7, v7, v8
	v_add_f32_e32 v8, v12, v7
	v_rcp_f32_e32 v13, v8
	v_add_f32_e32 v11, v9, v10
	v_sub_f32_e32 v9, v11, v9
	v_sub_f32_e32 v9, v10, v9
	v_sub_f32_e32 v10, v8, v12
	v_sub_f32_e32 v7, v7, v10
	v_mul_f32_e32 v10, v11, v13
	v_mul_f32_e32 v12, v8, v10
	v_fma_f32 v14, v10, v8, -v12
	v_fmac_f32_e32 v14, v10, v7
	v_add_f32_e32 v15, v12, v14
	v_sub_f32_e32 v16, v11, v15
	v_sub_f32_e32 v11, v11, v16
	v_sub_f32_e32 v12, v15, v12
	v_sub_f32_e32 v11, v11, v15
	v_add_f32_e32 v9, v9, v11
	v_sub_f32_e32 v11, v12, v14
	v_add_f32_e32 v9, v11, v9
	v_add_f32_e32 v11, v16, v9
	v_mul_f32_e32 v12, v13, v11
	v_mul_f32_e32 v14, v8, v12
	v_fma_f32 v8, v12, v8, -v14
	v_fmac_f32_e32 v8, v12, v7
	v_sub_f32_e32 v7, v16, v11
	v_add_f32_e32 v7, v9, v7
	v_add_f32_e32 v9, v14, v8
	v_sub_f32_e32 v15, v11, v9
	v_sub_f32_e32 v11, v11, v15
	v_sub_f32_e32 v14, v9, v14
	v_sub_f32_e32 v9, v11, v9
	v_add_f32_e32 v7, v7, v9
	v_sub_f32_e32 v8, v14, v8
	v_cvt_f32_i32_e32 v6, v6
	v_add_f32_e32 v7, v8, v7
	v_add_f32_e32 v8, v10, v12
	v_add_f32_e32 v7, v15, v7
	v_sub_f32_e32 v9, v8, v10
	v_mul_f32_e32 v7, v13, v7
	v_sub_f32_e32 v9, v12, v9
	v_add_f32_e32 v7, v9, v7
	v_mul_f32_e32 v12, 0x3f317218, v6
	s_mov_b32 s8, 0x3f317218
	v_add_f32_e32 v9, v8, v7
	v_fma_f32 v13, v6, s8, -v12
	v_mul_f32_e32 v10, v9, v9
	v_fmac_f32_e32 v13, 0xb102e308, v6
	v_sub_f32_e32 v6, v9, v8
	v_fmamk_f32 v11, v10, 0x3e9b6dac, v134
	v_sub_f32_e32 v6, v7, v6
	v_add_f32_e32 v7, v12, v13
	v_fmaak_f32 v11, v10, v11, 0x3f2aaada
	v_sub_f32_e32 v8, v7, v12
	v_ldexp_f32 v12, v9, 1
	v_mul_f32_e32 v9, v9, v10
	v_mul_f32_e32 v9, v9, v11
	v_add_f32_e32 v10, v12, v9
	v_sub_f32_e32 v11, v10, v12
	v_ldexp_f32 v6, v6, 1
	v_sub_f32_e32 v9, v9, v11
	v_add_f32_e32 v6, v6, v9
	v_add_f32_e32 v9, v10, v6
	v_sub_f32_e32 v10, v9, v10
	v_sub_f32_e32 v6, v6, v10
	v_add_f32_e32 v10, v7, v9
	v_sub_f32_e32 v11, v10, v7
	v_sub_f32_e32 v12, v10, v11
	v_sub_f32_e32 v8, v13, v8
	v_sub_f32_e32 v7, v7, v12
	v_sub_f32_e32 v9, v9, v11
	v_add_f32_e32 v7, v9, v7
	v_add_f32_e32 v9, v8, v6
	v_sub_f32_e32 v11, v9, v8
	v_sub_f32_e32 v12, v9, v11
	v_sub_f32_e32 v8, v8, v12
	v_sub_f32_e32 v6, v6, v11
	v_add_f32_e32 v7, v9, v7
	v_add_f32_e32 v6, v6, v8
	v_add_f32_e32 v8, v10, v7
	v_sub_f32_e32 v9, v8, v10
	v_sub_f32_e32 v7, v7, v9
	v_add_f32_e32 v6, v6, v7
	s_mov_b32 s8, 0x7f800000
	v_add_f32_e32 v6, v8, v6
	v_cmp_neq_f32_e32 vcc, s8, v4
	s_mov_b32 s8, 0x33800000
	s_mov_b32 s49, 0
	v_cndmask_b32_e32 v6, v137, v6, vcc
	v_cmp_ngt_f32_e32 vcc, -1.0, v4
	v_add_u32_e32 v208, s74, v105
	v_mov_b32_e32 v209, v123
	v_cndmask_b32_e32 v6, v138, v6, vcc
	v_cmp_neq_f32_e32 vcc, -1.0, v4
	v_mov_b32_e32 v205, 0
	v_mov_b32_e32 v203, 0
	v_cndmask_b32_e32 v6, v139, v6, vcc
	v_cmp_lt_f32_e64 vcc, |v4|, s8
	v_mov_b32_e32 v202, 0
	v_mov_b32_e32 v200, 0
	v_cndmask_b32_e32 v4, v6, v4, vcc
	s_cselect_b64 vcc, -1, 0
	v_cndmask_b32_e32 v5, v5, v75, vcc
	s_cmp_gt_i32 s33, 2
	s_waitcnt vmcnt(12)
	v_fmac_f32_e32 v73, v72, v5
	s_cselect_b64 vcc, -1, 0
	v_cndmask_b32_e32 v5, v5, v73, vcc
	s_cmp_gt_i32 s33, 3
	s_waitcnt vmcnt(11)
	v_fmac_f32_e32 v69, v68, v5
	s_cselect_b64 vcc, -1, 0
	v_cndmask_b32_e32 v5, v5, v69, vcc
	s_cmp_gt_i32 s33, 4
	s_waitcnt vmcnt(10)
	v_fmac_f32_e32 v71, v70, v5
	s_cselect_b64 vcc, -1, 0
	v_cndmask_b32_e32 v5, v5, v71, vcc
	s_cmp_gt_i32 s33, 5
	s_waitcnt vmcnt(9)
	v_fmac_f32_e32 v83, v82, v5
	s_cselect_b64 vcc, -1, 0
	v_cndmask_b32_e32 v5, v5, v83, vcc
	s_cmp_gt_i32 s33, 6
	s_waitcnt vmcnt(8)
	v_fmac_f32_e32 v81, v80, v5
	s_cselect_b64 vcc, -1, 0
	v_cndmask_b32_e32 v5, v5, v81, vcc
	s_cmp_gt_i32 s33, 7
	s_waitcnt vmcnt(7)
	v_fmac_f32_e32 v77, v76, v5
	s_cselect_b64 vcc, -1, 0
	v_cndmask_b32_e32 v5, v5, v77, vcc
	s_cmp_gt_i32 s33, 8
	s_waitcnt vmcnt(6)
	v_fmac_f32_e32 v79, v78, v5
	s_cselect_b64 vcc, -1, 0
	v_cndmask_b32_e32 v5, v5, v79, vcc
	s_cmp_gt_i32 s33, 9
	s_waitcnt vmcnt(5)
	v_fmac_f32_e32 v91, v90, v5
	s_cselect_b64 vcc, -1, 0
	v_cndmask_b32_e32 v5, v5, v91, vcc
	s_cmp_gt_i32 s33, 10
	s_waitcnt vmcnt(4)
	v_fmac_f32_e32 v89, v88, v5
	s_cselect_b64 vcc, -1, 0
	v_cndmask_b32_e32 v5, v5, v89, vcc
	s_cmp_gt_i32 s33, 11
	s_waitcnt vmcnt(3)
	v_fmac_f32_e32 v85, v84, v5
	s_cselect_b64 vcc, -1, 0
	v_cndmask_b32_e32 v5, v5, v85, vcc
	s_cmp_gt_i32 s33, 12
	s_waitcnt vmcnt(2)
	v_fmac_f32_e32 v87, v86, v5
	s_cselect_b64 vcc, -1, 0
	v_cndmask_b32_e32 v5, v5, v87, vcc
	s_cmp_gt_i32 s33, 13
	s_waitcnt vmcnt(1)
	v_fmac_f32_e32 v131, v130, v5
	s_cselect_b64 vcc, -1, 0
	v_cndmask_b32_e32 v5, v5, v131, vcc
	s_cmp_gt_i32 s33, 14
	s_waitcnt vmcnt(0)
	v_fmac_f32_e32 v129, v128, v5
	s_cselect_b64 vcc, -1, 0
	v_cndmask_b32_e32 v210, v5, v129, vcc
	v_mul_f32_e32 v207, 0xc1000000, v4
	v_or_b32_e32 v128, 64, v140
	v_or_b32_e32 v129, 0x80, v140
	v_or_b32_e32 v130, 0xc0, v140
	v_mov_b32_e32 v198, 0
	v_mov_b32_e32 v133, 0
	v_mov_b32_e32 v143, 0
	v_mov_b32_e32 v145, 0
	v_mov_b32_e32 v146, 0
	v_mov_b32_e32 v131, 0
	v_mov_b32_e32 v132, 0
	v_mov_b32_e32 v4, 0
	v_mov_b32_e32 v5, 0
	v_mov_b32_e32 v6, 0
	v_mov_b32_e32 v7, 0
	v_mov_b32_e32 v8, 0
	v_mov_b32_e32 v9, 0
	v_mov_b32_e32 v10, 0
	v_mov_b32_e32 v11, 0
	v_mov_b32_e32 v12, 0
	v_mov_b32_e32 v13, 0
	v_mov_b32_e32 v147, 0
	v_mov_b32_e32 v148, 0
	v_mov_b32_e32 v149, 0
	v_mov_b32_e32 v150, 0
	v_mov_b32_e32 v151, 0
	v_mov_b32_e32 v152, 0
	v_mov_b32_e32 v153, 0
	v_mov_b32_e32 v154, 0
	v_mov_b32_e32 v155, 0
	v_mov_b32_e32 v156, 0
	v_mov_b32_e32 v157, 0
	v_mov_b32_e32 v158, 0
	v_mov_b32_e32 v159, 0
	v_mov_b32_e32 v160, 0
	v_mov_b32_e32 v161, 0
	v_mov_b32_e32 v162, 0
	v_mov_b32_e32 v163, 0
	v_mov_b32_e32 v164, 0
	v_mov_b32_e32 v165, 0
	v_mov_b32_e32 v166, 0
	v_mov_b32_e32 v167, 0
	v_mov_b32_e32 v168, 0
	v_mov_b32_e32 v169, 0
	v_mov_b32_e32 v170, 0
	v_mov_b32_e32 v171, 0
	v_mov_b32_e32 v172, 0
	v_readfirstlane_b32 s98, v144
	s_cmp_lt_u32 s98, 0x100
	s_cbranch_scc1 .Lstag_708
	s_sleep 32

; template <bool PASS2>
; __device__ __forceinline__ void lru_item(const Frame& F, const Args& a, int item) {
;     ...
;         const bf16_t* wt = (const bf16_t*)(a.ws + WS_WLRU) + (size_t)((dir * 12 + n) * 2) * 16384 + (size_t)c * 128 + 8 * fq;
;         bf16x8 wrf[4], wif[4];
; #pragma unroll
;         for (int ks = 0; ks < 4; ++ks) { wrf[ks] = *(const bf16x8*)(wt + 32 * ks); wif[ks] = *(const bf16x8*)(wt + 16384 + 32 * ks); }
;         const float ba = a.lru_ba[dir * 1536 + cg_], bi = a.lru_bi[dir * 1536 + cg_];
;         const float lam = a.lru_lambda[dir * 1536 + cg_];
;         const float logu = -8.0f * log1pf(__expf(-lam));
;         float hc = 0.f, TA = 1.f, TB = 0.f;
;         if (PASS2) { const f32x2* ag = (const f32x2*)(a.ws + WS_AGG) + ((size_t)(b * NCHUNK) * 2 + dir) * 1536 + cg_;
;             f32x2 pa[NCHUNK];
; #pragma unroll
;             for (int cc = 0; cc < NCHUNK; ++cc) pa[cc] = ag[(size_t)cc * 2 * 1536];
; #pragma unroll
;             for (int i = 0; i < NCHUNK; ++i) { const int cc = dir ? NCHUNK - 1 - i : i; const bool use = dir ? (cc > chunk) : (cc < chunk); if (use) hc = pa[cc].x * hc + pa[cc].y; } }
;         const int tstart = dir ? SEQ - 1 : 0;
;         if (dir == 1) __syncthreads();
; #pragma unroll 1
;         for (int si = 0; si < 4; ++si) { const int s = dir ? 3 - si : si;
.LBB0_744:
	s_waitcnt vmcnt(16)
	v_mul_f32_e32 v66, 0xbfb8aa3b, v70
	v_exp_f32_e32 v66, v66
	s_mov_b32 s3, 0x3f2aaaab
	s_cmp_lt_i32 s33, 14
	s_waitcnt vmcnt(0)
	v_fmac_f32_e32 v65, v64, v67
	v_add_f32_e32 v70, 1.0, v66
	v_frexp_mant_f32_e32 v72, v70
	v_cvt_f64_f32_e32 v[68:69], v70
	v_add_f32_e32 v71, -1.0, v70
	v_frexp_exp_i32_f64_e32 v68, v[68:69]
	v_cmp_gt_f32_e32 vcc, s3, v72
	v_sub_f32_e32 v73, v71, v70
	v_sub_f32_e32 v71, v66, v71
	v_subbrev_co_u32_e32 v68, vcc, 0, v68, vcc
	v_add_f32_e32 v73, 1.0, v73
	v_sub_u32_e32 v69, 0, v68
	v_add_f32_e32 v71, v71, v73
	v_ldexp_f32 v70, v70, v69
	v_ldexp_f32 v69, v71, v69
	v_add_f32_e32 v71, -1.0, v70
	v_add_f32_e32 v74, 1.0, v70
	v_add_f32_e32 v72, 1.0, v71
	v_add_f32_e32 v75, -1.0, v74
	v_sub_f32_e32 v72, v70, v72
	v_sub_f32_e32 v70, v70, v75
	v_add_f32_e32 v72, v69, v72
	v_add_f32_e32 v69, v69, v70
	v_add_f32_e32 v70, v74, v69
	v_rcp_f32_e32 v75, v70
	v_add_f32_e32 v73, v71, v72
	v_sub_f32_e32 v71, v73, v71
	v_sub_f32_e32 v71, v72, v71
	v_sub_f32_e32 v72, v70, v74
	v_sub_f32_e32 v69, v69, v72
	v_mul_f32_e32 v72, v73, v75
	v_mul_f32_e32 v74, v70, v72
	v_fma_f32 v76, v72, v70, -v74
	v_fmac_f32_e32 v76, v72, v69
	v_add_f32_e32 v77, v74, v76
	v_sub_f32_e32 v78, v73, v77
	v_sub_f32_e32 v73, v73, v78
	v_sub_f32_e32 v74, v77, v74
	v_sub_f32_e32 v73, v73, v77
	v_add_f32_e32 v71, v71, v73
	v_sub_f32_e32 v73, v74, v76
	v_add_f32_e32 v71, v73, v71
	v_add_f32_e32 v73, v78, v71
	v_mul_f32_e32 v74, v75, v73
	v_mul_f32_e32 v76, v70, v74
	v_fma_f32 v70, v74, v70, -v76
	v_fmac_f32_e32 v70, v74, v69
	v_sub_f32_e32 v69, v78, v73
	v_add_f32_e32 v69, v71, v69
	v_add_f32_e32 v71, v76, v70
	v_sub_f32_e32 v77, v73, v71
	v_sub_f32_e32 v73, v73, v77
	v_sub_f32_e32 v76, v71, v76
	v_sub_f32_e32 v71, v73, v71
	v_add_f32_e32 v69, v69, v71
	v_sub_f32_e32 v70, v76, v70
	v_cvt_f32_i32_e32 v68, v68
	v_add_f32_e32 v69, v70, v69
	v_add_f32_e32 v70, v72, v74
	v_add_f32_e32 v69, v77, v69
	v_sub_f32_e32 v71, v70, v72
	v_mul_f32_e32 v69, v75, v69
	v_sub_f32_e32 v71, v74, v71
	v_add_f32_e32 v69, v71, v69
	v_mul_f32_e32 v74, 0x3f317218, v68
	s_mov_b32 s3, 0x3f317218
	v_add_f32_e32 v71, v70, v69
	v_fma_f32 v75, v68, s3, -v74
	v_mul_f32_e32 v72, v71, v71
	v_fmac_f32_e32 v75, 0xb102e308, v68
	v_sub_f32_e32 v68, v71, v70
	v_fmamk_f32 v73, v72, 0x3e9b6dac, v134
	v_sub_f32_e32 v68, v69, v68
	v_add_f32_e32 v69, v74, v75
	v_fmaak_f32 v73, v72, v73, 0x3f2aaada
	v_sub_f32_e32 v70, v69, v74
	v_ldexp_f32 v74, v71, 1
	v_mul_f32_e32 v71, v71, v72
	v_mul_f32_e32 v71, v71, v73
	v_add_f32_e32 v72, v74, v71
	v_sub_f32_e32 v73, v72, v74
	v_ldexp_f32 v68, v68, 1
	v_sub_f32_e32 v71, v71, v73
	v_add_f32_e32 v68, v68, v71
	v_add_f32_e32 v71, v72, v68
	v_sub_f32_e32 v72, v71, v72
	v_sub_f32_e32 v68, v68, v72
	v_add_f32_e32 v72, v69, v71
	v_sub_f32_e32 v73, v72, v69
	v_sub_f32_e32 v74, v72, v73
	v_sub_f32_e32 v70, v75, v70
	v_sub_f32_e32 v69, v69, v74
	v_sub_f32_e32 v71, v71, v73
	v_add_f32_e32 v69, v71, v69
	v_add_f32_e32 v71, v70, v68
	v_sub_f32_e32 v73, v71, v70
	v_sub_f32_e32 v74, v71, v73
	v_sub_f32_e32 v70, v70, v74
	v_sub_f32_e32 v68, v68, v73
	v_add_f32_e32 v69, v71, v69
	v_add_f32_e32 v68, v68, v70
	v_add_f32_e32 v70, v72, v69
	v_sub_f32_e32 v71, v70, v72
	v_sub_f32_e32 v69, v69, v71
	v_add_f32_e32 v68, v68, v69
	s_mov_b32 s3, 0x7f800000
	v_add_f32_e32 v68, v70, v68
	v_cmp_neq_f32_e32 vcc, s3, v66
	s_mov_b32 s3, 0x33800000
	s_mov_b32 s2, 0
	v_cndmask_b32_e32 v68, v137, v68, vcc
	v_cmp_ngt_f32_e32 vcc, -1.0, v66
	s_barrier
	s_nop 0
	v_cndmask_b32_e32 v68, v138, v68, vcc
	v_cmp_neq_f32_e32 vcc, -1.0, v66
	s_nop 1
	v_cndmask_b32_e32 v68, v139, v68, vcc
	v_cmp_lt_f32_e64 vcc, |v66|, s3
	s_nop 1
	v_cndmask_b32_e32 v66, v68, v66, vcc
	s_cselect_b64 vcc, -1, 0
	v_cndmask_b32_e32 v64, v67, v65, vcc
	s_cmp_lt_i32 s33, 13
	v_fmac_f32_e32 v63, v62, v64
	s_cselect_b64 vcc, -1, 0
	v_cndmask_b32_e32 v62, v64, v63, vcc
	s_cmp_lt_i32 s33, 12
	v_fmac_f32_e32 v61, v60, v62
	s_cselect_b64 vcc, -1, 0
	v_cndmask_b32_e32 v60, v62, v61, vcc
	s_cmp_lt_i32 s33, 11
	v_fmac_f32_e32 v59, v58, v60
	s_cselect_b64 vcc, -1, 0
	v_cndmask_b32_e32 v58, v60, v59, vcc
	s_cmp_lt_i32 s33, 10
	v_fmac_f32_e32 v57, v56, v58
	s_cselect_b64 vcc, -1, 0
	v_cndmask_b32_e32 v56, v58, v57, vcc
	s_cmp_lt_i32 s33, 9
	v_fmac_f32_e32 v55, v54, v56
	s_cselect_b64 vcc, -1, 0
	v_cndmask_b32_e32 v54, v56, v55, vcc
	s_cmp_lt_i32 s33, 8
	v_fmac_f32_e32 v53, v52, v54
	s_cselect_b64 vcc, -1, 0
	v_cndmask_b32_e32 v52, v54, v53, vcc
	s_cmp_lt_i32 s33, 7
	v_fmac_f32_e32 v51, v50, v52
	s_cselect_b64 vcc, -1, 0
	v_cndmask_b32_e32 v50, v52, v51, vcc
	s_cmp_lt_i32 s33, 6
	v_fmac_f32_e32 v49, v48, v50
	s_cselect_b64 vcc, -1, 0
	v_cndmask_b32_e32 v48, v50, v49, vcc
	s_cmp_lt_i32 s33, 5
	v_fmac_f32_e32 v47, v46, v48
	s_cselect_b64 vcc, -1, 0
	v_cndmask_b32_e32 v46, v48, v47, vcc
	s_cmp_lt_i32 s33, 4
	v_fmac_f32_e32 v45, v44, v46
	s_cselect_b64 vcc, -1, 0
	v_cndmask_b32_e32 v44, v46, v45, vcc
	s_cmp_lt_i32 s33, 3
	v_fmac_f32_e32 v43, v42, v44
	s_cselect_b64 vcc, -1, 0
	v_cndmask_b32_e32 v42, v44, v43, vcc
	s_cmp_lt_i32 s33, 2
	v_fmac_f32_e32 v41, v40, v42
	s_cselect_b64 vcc, -1, 0
	v_cndmask_b32_e32 v40, v42, v41, vcc
	s_cmp_lt_i32 s33, 1
	v_fmac_f32_e32 v39, v38, v40
	s_cselect_b64 vcc, -1, 0
	v_cndmask_b32_e32 v38, v40, v39, vcc
	s_cmp_lt_i32 s33, 0
	v_fmac_f32_e32 v37, v36, v38
	s_cselect_b64 vcc, -1, 0
	v_cndmask_b32_e32 v127, v38, v37, vcc
	v_mul_f32_e32 v126, 0xc1000000, v66
	v_readfirstlane_b32 s98, v144
	s_cmp_lt_u32 s98, 0x100
	s_cbranch_scc1 .Lstag_746
	s_sleep 32

; template <bool PASS2>
; __device__ __forceinline__ void lru_item(const Frame& F, const Args& a, int item) {
;     ...
;         const float ba = a.lru_ba[dir * 1536 + cg_], bi = a.lru_bi[dir * 1536 + cg_];
;         const float lam = a.lru_lambda[dir * 1536 + cg_];
;         const float logu = -8.0f * log1pf(__expf(-lam));
;         float hc = 0.f, TA = 1.f, TB = 0.f;
;         if (PASS2) { const f32x2* ag = (const f32x2*)(a.ws + WS_AGG) + ((size_t)(b * NCHUNK) * 2 + dir) * 1536 + cg_;
;             f32x2 pa[NCHUNK];
; #pragma unroll
;             for (int cc = 0; cc < NCHUNK; ++cc) pa[cc] = ag[(size_t)cc * 2 * 1536];
; #pragma unroll
;             for (int i = 0; i < NCHUNK; ++i) { const int cc = dir ? NCHUNK - 1 - i : i; const bool use = dir ? (cc > chunk) : (cc < chunk); if (use) hc = pa[cc].x * hc + pa[cc].y; } }
;         const int tstart = dir ? SEQ - 1 : 0;
;         if (dir == 1) __syncthreads();
; #pragma unroll 1
;         for (int si = 0; si < 4; ++si) { const int s = dir ? 3 - si : si;
.LBB0_826:
	s_waitcnt vmcnt(15)
	v_mul_f32_e32 v36, 0xbfb8aa3b, v125
	v_exp_f32_e32 v36, v36
	s_cmp_gt_i32 s80, 1
	s_waitcnt vmcnt(13)
	v_fmac_f32_e32 v75, v74, v37
	s_mov_b32 s82, 0
	v_add_f32_e32 v40, 1.0, v36
	v_frexp_mant_f32_e32 v42, v40
	v_cvt_f64_f32_e32 v[38:39], v40
	v_add_f32_e32 v41, -1.0, v40
	v_frexp_exp_i32_f64_e32 v38, v[38:39]
	v_cmp_gt_f32_e32 vcc, s55, v42
	v_sub_f32_e32 v43, v41, v40
	v_sub_f32_e32 v41, v36, v41
	v_subbrev_co_u32_e32 v38, vcc, 0, v38, vcc
	v_add_f32_e32 v43, 1.0, v43
	v_sub_u32_e32 v39, 0, v38
	v_add_f32_e32 v41, v41, v43
	v_ldexp_f32 v40, v40, v39
	v_ldexp_f32 v39, v41, v39
	v_add_f32_e32 v41, -1.0, v40
	v_add_f32_e32 v44, 1.0, v40
	v_add_f32_e32 v42, 1.0, v41
	v_add_f32_e32 v45, -1.0, v44
	v_sub_f32_e32 v42, v40, v42
	v_sub_f32_e32 v40, v40, v45
	v_add_f32_e32 v42, v39, v42
	v_add_f32_e32 v39, v39, v40
	v_add_f32_e32 v40, v44, v39
	v_rcp_f32_e32 v45, v40
	v_add_f32_e32 v43, v41, v42
	v_sub_f32_e32 v41, v43, v41
	v_sub_f32_e32 v41, v42, v41
	v_sub_f32_e32 v42, v40, v44
	v_sub_f32_e32 v39, v39, v42
	v_mul_f32_e32 v42, v43, v45
	v_mul_f32_e32 v44, v40, v42
	v_fma_f32 v46, v42, v40, -v44
	v_fmac_f32_e32 v46, v42, v39
	v_add_f32_e32 v47, v44, v46
	v_sub_f32_e32 v48, v43, v47
	v_sub_f32_e32 v43, v43, v48
	v_sub_f32_e32 v44, v47, v44
	v_sub_f32_e32 v43, v43, v47
	v_add_f32_e32 v41, v41, v43
	v_sub_f32_e32 v43, v44, v46
	v_add_f32_e32 v41, v43, v41
	v_add_f32_e32 v43, v48, v41
	v_mul_f32_e32 v44, v45, v43
	v_mul_f32_e32 v46, v40, v44
	v_fma_f32 v40, v44, v40, -v46
	v_fmac_f32_e32 v40, v44, v39
	v_sub_f32_e32 v39, v48, v43
	v_add_f32_e32 v39, v41, v39
	v_add_f32_e32 v41, v46, v40
	v_sub_f32_e32 v47, v43, v41
	v_sub_f32_e32 v43, v43, v47
	v_sub_f32_e32 v46, v41, v46
	v_sub_f32_e32 v41, v43, v41
	v_add_f32_e32 v39, v39, v41
	v_sub_f32_e32 v40, v46, v40
	v_cvt_f32_i32_e32 v38, v38
	v_add_f32_e32 v39, v40, v39
	v_add_f32_e32 v40, v42, v44
	v_add_f32_e32 v39, v47, v39
	v_sub_f32_e32 v41, v40, v42
	v_mul_f32_e32 v39, v45, v39
	v_sub_f32_e32 v41, v44, v41
	v_add_f32_e32 v39, v41, v39
	v_mul_f32_e32 v44, 0x3f317218, v38
	v_add_f32_e32 v41, v40, v39
	v_fma_f32 v45, v38, s56, -v44
	v_mul_f32_e32 v42, v41, v41
	v_fmac_f32_e32 v45, 0xb102e308, v38
	v_sub_f32_e32 v38, v41, v40
	v_fmamk_f32 v43, v42, 0x3e9b6dac, v123
	v_sub_f32_e32 v38, v39, v38
	v_add_f32_e32 v39, v44, v45
	v_fmaak_f32 v43, v42, v43, 0x3f2aaada
	v_sub_f32_e32 v40, v39, v44
	v_ldexp_f32 v44, v41, 1
	v_mul_f32_e32 v41, v41, v42
	v_mul_f32_e32 v41, v41, v43
	v_add_f32_e32 v42, v44, v41
	v_sub_f32_e32 v43, v42, v44
	v_ldexp_f32 v38, v38, 1
	v_sub_f32_e32 v41, v41, v43
	v_add_f32_e32 v38, v38, v41
	v_add_f32_e32 v41, v42, v38
	v_sub_f32_e32 v42, v41, v42
	v_sub_f32_e32 v38, v38, v42
	v_add_f32_e32 v42, v39, v41
	v_sub_f32_e32 v43, v42, v39
	v_sub_f32_e32 v44, v42, v43
	v_sub_f32_e32 v40, v45, v40
	v_sub_f32_e32 v39, v39, v44
	v_sub_f32_e32 v41, v41, v43
	v_add_f32_e32 v39, v41, v39
	v_add_f32_e32 v41, v40, v38
	v_sub_f32_e32 v43, v41, v40
	v_sub_f32_e32 v44, v41, v43
	v_sub_f32_e32 v40, v40, v44
	v_sub_f32_e32 v38, v38, v43
	v_add_f32_e32 v39, v41, v39
	v_add_f32_e32 v38, v38, v40
	v_add_f32_e32 v40, v42, v39
	v_sub_f32_e32 v41, v40, v42
	v_sub_f32_e32 v39, v39, v41
	v_add_f32_e32 v38, v38, v39
	v_add_f32_e32 v38, v40, v38
	v_cmp_neq_f32_e32 vcc, s57, v36
	v_add_u32_e32 v208, s79, v103
	v_mov_b32_e32 v209, v121
	v_cndmask_b32_e32 v38, v136, v38, vcc
	v_cmp_ngt_f32_e32 vcc, -1.0, v36
	v_mov_b32_e32 v205, 0
	v_mov_b32_e32 v203, 0
	v_cndmask_b32_e32 v38, v137, v38, vcc
	v_cmp_neq_f32_e32 vcc, -1.0, v36
	v_mov_b32_e32 v202, 0
	v_mov_b32_e32 v200, 0
	v_cndmask_b32_e32 v38, v138, v38, vcc
	v_cmp_lt_f32_e64 vcc, |v36|, s58
	v_mov_b32_e32 v198, 0
	v_mov_b32_e32 v133, 0
	v_cndmask_b32_e32 v36, v38, v36, vcc
	s_cselect_b64 vcc, -1, 0
	v_cndmask_b32_e32 v37, v37, v75, vcc
	s_cmp_gt_i32 s80, 2
	s_waitcnt vmcnt(12)
	v_fmac_f32_e32 v73, v72, v37
	s_cselect_b64 vcc, -1, 0
	v_cndmask_b32_e32 v37, v37, v73, vcc
	s_cmp_gt_i32 s80, 3
	s_waitcnt vmcnt(11)
	v_fmac_f32_e32 v69, v68, v37
	s_cselect_b64 vcc, -1, 0
	v_cndmask_b32_e32 v37, v37, v69, vcc
	s_cmp_gt_i32 s80, 4
	s_waitcnt vmcnt(10)
	v_fmac_f32_e32 v71, v70, v37
	s_cselect_b64 vcc, -1, 0
	v_cndmask_b32_e32 v37, v37, v71, vcc
	s_cmp_gt_i32 s80, 5
	s_waitcnt vmcnt(9)
	v_fmac_f32_e32 v83, v82, v37
	s_cselect_b64 vcc, -1, 0
	v_cndmask_b32_e32 v37, v37, v83, vcc
	s_cmp_gt_i32 s80, 6
	s_waitcnt vmcnt(8)
	v_fmac_f32_e32 v81, v80, v37
	s_cselect_b64 vcc, -1, 0
	v_cndmask_b32_e32 v37, v37, v81, vcc
	s_cmp_gt_i32 s80, 7
	s_waitcnt vmcnt(7)
	v_fmac_f32_e32 v77, v76, v37
	s_cselect_b64 vcc, -1, 0
	v_cndmask_b32_e32 v37, v37, v77, vcc
	s_cmp_gt_i32 s80, 8
	s_waitcnt vmcnt(6)
	v_fmac_f32_e32 v79, v78, v37
	s_cselect_b64 vcc, -1, 0
	v_cndmask_b32_e32 v37, v37, v79, vcc
	s_cmp_gt_i32 s80, 9
	s_waitcnt vmcnt(5)
	v_fmac_f32_e32 v91, v90, v37
	s_cselect_b64 vcc, -1, 0
	v_cndmask_b32_e32 v37, v37, v91, vcc
	s_cmp_gt_i32 s80, 10
	s_waitcnt vmcnt(4)
	v_fmac_f32_e32 v89, v88, v37
	s_cselect_b64 vcc, -1, 0
	v_cndmask_b32_e32 v37, v37, v89, vcc
	s_cmp_gt_i32 s80, 11
	s_waitcnt vmcnt(3)
	v_fmac_f32_e32 v85, v84, v37
	s_cselect_b64 vcc, -1, 0
	v_cndmask_b32_e32 v37, v37, v85, vcc
	s_cmp_gt_i32 s80, 12
	s_waitcnt vmcnt(2)
	v_fmac_f32_e32 v87, v86, v37
	s_cselect_b64 vcc, -1, 0
	v_cndmask_b32_e32 v37, v37, v87, vcc
	s_cmp_gt_i32 s80, 13
	s_waitcnt vmcnt(1)
	v_fmac_f32_e32 v131, v130, v37
	s_cselect_b64 vcc, -1, 0
	v_cndmask_b32_e32 v37, v37, v131, vcc
	s_cmp_gt_i32 s80, 14
	s_waitcnt vmcnt(0)
	v_fmac_f32_e32 v129, v128, v37
	s_cselect_b64 vcc, -1, 0
	v_cndmask_b32_e32 v210, v37, v129, vcc
	v_mul_f32_e32 v207, 0xc1000000, v36
	v_or_b32_e32 v128, 64, v139
	v_or_b32_e32 v129, 0x80, v139
	v_or_b32_e32 v130, 0xc0, v139
	v_mov_b32_e32 v142, 0
	v_mov_b32_e32 v143, 0
	v_mov_b32_e32 v146, 0
	v_mov_b32_e32 v131, 0
	v_mov_b32_e32 v132, 0
	v_mov_b32_e32 v36, 0
	v_mov_b32_e32 v37, 0
	v_mov_b32_e32 v38, 0
	v_mov_b32_e32 v39, 0
	v_mov_b32_e32 v40, 0
	v_mov_b32_e32 v41, 0
	v_mov_b32_e32 v42, 0
	v_mov_b32_e32 v43, 0
	v_mov_b32_e32 v44, 0
	v_mov_b32_e32 v45, 0
	v_mov_b32_e32 v147, 0
	v_mov_b32_e32 v148, 0
	v_mov_b32_e32 v149, 0
	v_mov_b32_e32 v150, 0
	v_mov_b32_e32 v151, 0
	v_mov_b32_e32 v152, 0
	v_mov_b32_e32 v153, 0
	v_mov_b32_e32 v154, 0
	v_mov_b32_e32 v155, 0
	v_mov_b32_e32 v156, 0
	v_mov_b32_e32 v157, 0
	v_mov_b32_e32 v158, 0
	v_mov_b32_e32 v159, 0
	v_mov_b32_e32 v160, 0
	v_mov_b32_e32 v161, 0
	v_mov_b32_e32 v162, 0
	v_mov_b32_e32 v163, 0
	v_mov_b32_e32 v164, 0
	v_mov_b32_e32 v165, 0
	v_mov_b32_e32 v166, 0
	v_mov_b32_e32 v167, 0
	v_mov_b32_e32 v168, 0
	v_mov_b32_e32 v169, 0
	v_mov_b32_e32 v170, 0
	v_mov_b32_e32 v171, 0
	v_mov_b32_e32 v172, 0
	v_readfirstlane_b32 s98, v144
	s_cmp_lt_u32 s98, 0x100
	s_cbranch_scc1 .Lstag_827
	s_sleep 32

; template <bool PASS2>
; __device__ __forceinline__ void lru_item(const Frame& F, const Args& a, int item) {
;     ...
;         const float ba = a.lru_ba[dir * 1536 + cg_], bi = a.lru_bi[dir * 1536 + cg_];
;         const float lam = a.lru_lambda[dir * 1536 + cg_];
;         const float logu = -8.0f * log1pf(__expf(-lam));
;         float hc = 0.f, TA = 1.f, TB = 0.f;
;         if (PASS2) { const f32x2* ag = (const f32x2*)(a.ws + WS_AGG) + ((size_t)(b * NCHUNK) * 2 + dir) * 1536 + cg_;
;             f32x2 pa[NCHUNK];
; #pragma unroll
;             for (int cc = 0; cc < NCHUNK; ++cc) pa[cc] = ag[(size_t)cc * 2 * 1536];
; #pragma unroll
;             for (int i = 0; i < NCHUNK; ++i) { const int cc = dir ? NCHUNK - 1 - i : i; const bool use = dir ? (cc > chunk) : (cc < chunk); if (use) hc = pa[cc].x * hc + pa[cc].y; } }
;         const int tstart = dir ? SEQ - 1 : 0;
;         if (dir == 1) __syncthreads();
; #pragma unroll 1
;         for (int si = 0; si < 4; ++si) { const int s = dir ? 3 - si : si;
.LBB0_863:
	s_waitcnt vmcnt(16)
	v_mul_f32_e32 v66, 0xbfb8aa3b, v70
	v_exp_f32_e32 v66, v66
	s_cmp_lt_i32 s80, 14
	s_waitcnt vmcnt(0)
	v_fmac_f32_e32 v65, v64, v67
	s_mov_b32 s46, 0
	v_add_f32_e32 v70, 1.0, v66
	v_frexp_mant_f32_e32 v72, v70
	v_cvt_f64_f32_e32 v[68:69], v70
	v_add_f32_e32 v71, -1.0, v70
	v_frexp_exp_i32_f64_e32 v68, v[68:69]
	v_cmp_gt_f32_e32 vcc, s55, v72
	v_sub_f32_e32 v73, v71, v70
	v_sub_f32_e32 v71, v66, v71
	v_subbrev_co_u32_e32 v68, vcc, 0, v68, vcc
	v_add_f32_e32 v73, 1.0, v73
	v_sub_u32_e32 v69, 0, v68
	v_add_f32_e32 v71, v71, v73
	v_ldexp_f32 v70, v70, v69
	v_ldexp_f32 v69, v71, v69
	v_add_f32_e32 v71, -1.0, v70
	v_add_f32_e32 v74, 1.0, v70
	v_add_f32_e32 v72, 1.0, v71
	v_add_f32_e32 v75, -1.0, v74
	v_sub_f32_e32 v72, v70, v72
	v_sub_f32_e32 v70, v70, v75
	v_add_f32_e32 v72, v69, v72
	v_add_f32_e32 v69, v69, v70
	v_add_f32_e32 v70, v74, v69
	v_rcp_f32_e32 v75, v70
	v_add_f32_e32 v73, v71, v72
	v_sub_f32_e32 v71, v73, v71
	v_sub_f32_e32 v71, v72, v71
	v_sub_f32_e32 v72, v70, v74
	v_sub_f32_e32 v69, v69, v72
	v_mul_f32_e32 v72, v73, v75
	v_mul_f32_e32 v74, v70, v72
	v_fma_f32 v76, v72, v70, -v74
	v_fmac_f32_e32 v76, v72, v69
	v_add_f32_e32 v77, v74, v76
	v_sub_f32_e32 v78, v73, v77
	v_sub_f32_e32 v73, v73, v78
	v_sub_f32_e32 v74, v77, v74
	v_sub_f32_e32 v73, v73, v77
	v_add_f32_e32 v71, v71, v73
	v_sub_f32_e32 v73, v74, v76
	v_add_f32_e32 v71, v73, v71
	v_add_f32_e32 v73, v78, v71
	v_mul_f32_e32 v74, v75, v73
	v_mul_f32_e32 v76, v70, v74
	v_fma_f32 v70, v74, v70, -v76
	v_fmac_f32_e32 v70, v74, v69
	v_sub_f32_e32 v69, v78, v73
	v_add_f32_e32 v69, v71, v69
	v_add_f32_e32 v71, v76, v70
	v_sub_f32_e32 v77, v73, v71
	v_sub_f32_e32 v73, v73, v77
	v_sub_f32_e32 v76, v71, v76
	v_sub_f32_e32 v71, v73, v71
	v_add_f32_e32 v69, v69, v71
	v_sub_f32_e32 v70, v76, v70
	v_cvt_f32_i32_e32 v68, v68
	v_add_f32_e32 v69, v70, v69
	v_add_f32_e32 v70, v72, v74
	v_add_f32_e32 v69, v77, v69
	v_sub_f32_e32 v71, v70, v72
	v_mul_f32_e32 v69, v75, v69
	v_sub_f32_e32 v71, v74, v71
	v_add_f32_e32 v69, v71, v69
	v_mul_f32_e32 v74, 0x3f317218, v68
	v_add_f32_e32 v71, v70, v69
	v_fma_f32 v75, v68, s56, -v74
	v_mul_f32_e32 v72, v71, v71
	v_fmac_f32_e32 v75, 0xb102e308, v68
	v_sub_f32_e32 v68, v71, v70
	v_fmamk_f32 v73, v72, 0x3e9b6dac, v123
	v_sub_f32_e32 v68, v69, v68
	v_add_f32_e32 v69, v74, v75
	v_fmaak_f32 v73, v72, v73, 0x3f2aaada
	v_sub_f32_e32 v70, v69, v74
	v_ldexp_f32 v74, v71, 1
	v_mul_f32_e32 v71, v71, v72
	v_mul_f32_e32 v71, v71, v73
	v_add_f32_e32 v72, v74, v71
	v_sub_f32_e32 v73, v72, v74
	v_ldexp_f32 v68, v68, 1
	v_sub_f32_e32 v71, v71, v73
	v_add_f32_e32 v68, v68, v71
	v_add_f32_e32 v71, v72, v68
	v_sub_f32_e32 v72, v71, v72
	v_sub_f32_e32 v68, v68, v72
	v_add_f32_e32 v72, v69, v71
	v_sub_f32_e32 v73, v72, v69
	v_sub_f32_e32 v74, v72, v73
	v_sub_f32_e32 v70, v75, v70
	v_sub_f32_e32 v69, v69, v74
	v_sub_f32_e32 v71, v71, v73
	v_add_f32_e32 v69, v71, v69
	v_add_f32_e32 v71, v70, v68
	v_sub_f32_e32 v73, v71, v70
	v_sub_f32_e32 v74, v71, v73
	v_sub_f32_e32 v70, v70, v74
	v_sub_f32_e32 v68, v68, v73
	v_add_f32_e32 v69, v71, v69
	v_add_f32_e32 v68, v68, v70
	v_add_f32_e32 v70, v72, v69
	v_sub_f32_e32 v71, v70, v72
	v_sub_f32_e32 v69, v69, v71
	v_add_f32_e32 v68, v68, v69
	v_add_f32_e32 v68, v70, v68
	v_cmp_neq_f32_e32 vcc, s57, v66
	s_barrier
	s_nop 0
	v_cndmask_b32_e32 v68, v136, v68, vcc
	v_cmp_ngt_f32_e32 vcc, -1.0, v66
	s_nop 1
	v_cndmask_b32_e32 v68, v137, v68, vcc
	v_cmp_neq_f32_e32 vcc, -1.0, v66
	s_nop 1
	v_cndmask_b32_e32 v68, v138, v68, vcc
	v_cmp_lt_f32_e64 vcc, |v66|, s58
	s_nop 1
	v_cndmask_b32_e32 v66, v68, v66, vcc
	s_cselect_b64 vcc, -1, 0
	v_cndmask_b32_e32 v64, v67, v65, vcc
	s_cmp_lt_i32 s80, 13
	v_fmac_f32_e32 v63, v62, v64
	s_cselect_b64 vcc, -1, 0
	v_cndmask_b32_e32 v62, v64, v63, vcc
	s_cmp_lt_i32 s80, 12
	v_fmac_f32_e32 v61, v60, v62
	s_cselect_b64 vcc, -1, 0
	v_cndmask_b32_e32 v60, v62, v61, vcc
	s_cmp_lt_i32 s80, 11
	v_fmac_f32_e32 v59, v58, v60
	s_cselect_b64 vcc, -1, 0
	v_cndmask_b32_e32 v58, v60, v59, vcc
	s_cmp_lt_i32 s80, 10
	v_fmac_f32_e32 v57, v56, v58
	s_cselect_b64 vcc, -1, 0
	v_cndmask_b32_e32 v56, v58, v57, vcc
	s_cmp_lt_i32 s80, 9
	v_fmac_f32_e32 v55, v54, v56
	s_cselect_b64 vcc, -1, 0
	v_cndmask_b32_e32 v54, v56, v55, vcc
	s_cmp_lt_i32 s80, 8
	v_fmac_f32_e32 v53, v52, v54
	s_cselect_b64 vcc, -1, 0
	v_cndmask_b32_e32 v52, v54, v53, vcc
	s_cmp_lt_i32 s80, 7
	v_fmac_f32_e32 v51, v50, v52
	s_cselect_b64 vcc, -1, 0
	v_cndmask_b32_e32 v50, v52, v51, vcc
	s_cmp_lt_i32 s80, 6
	v_fmac_f32_e32 v49, v48, v50
	s_cselect_b64 vcc, -1, 0
	v_cndmask_b32_e32 v48, v50, v49, vcc
	s_cmp_lt_i32 s80, 5
	v_fmac_f32_e32 v47, v46, v48
	s_cselect_b64 vcc, -1, 0
	v_cndmask_b32_e32 v46, v48, v47, vcc
	s_cmp_lt_i32 s80, 4
	v_fmac_f32_e32 v45, v44, v46
	s_cselect_b64 vcc, -1, 0
	v_cndmask_b32_e32 v44, v46, v45, vcc
	s_cmp_lt_i32 s80, 3
	v_fmac_f32_e32 v43, v42, v44
	s_cselect_b64 vcc, -1, 0
	v_cndmask_b32_e32 v42, v44, v43, vcc
	s_cmp_lt_i32 s80, 2
	v_fmac_f32_e32 v41, v40, v42
	s_cselect_b64 vcc, -1, 0
	v_cndmask_b32_e32 v40, v42, v41, vcc
	s_cmp_lt_i32 s80, 1
	v_fmac_f32_e32 v39, v38, v40
	s_cselect_b64 vcc, -1, 0
	v_cndmask_b32_e32 v38, v40, v39, vcc
	s_cmp_lt_i32 s80, 0
	v_fmac_f32_e32 v37, v36, v38
	s_cselect_b64 vcc, -1, 0
	v_cndmask_b32_e32 v127, v38, v37, vcc
	v_mul_f32_e32 v126, 0xc1000000, v66
	v_readfirstlane_b32 s98, v144
	s_cmp_lt_u32 s98, 0x100
	s_cbranch_scc1 .Lstag_865
	s_sleep 32
